# cross-barrier prefetch: h3 phase's first f/q/i tile loads issued before the preceding grid-barrier wait
# speedup vs baseline: 1.0022x; 1.0022x over previous
.LBB0_297:
	s_and_b64 vcc, exec, s[8:9]
	s_cbranch_vccz .LBB0_400
	s_lshl_b32 s0, s35, 4
	s_lshl_b32 s1, s35, 6
	s_and_b32 s0, s0, 0x3000
	s_and_b32 s1, s1, 0xfc0
	s_or_b32 s0, s0, s1
	v_readlane_b32 s8, v251, 57
	v_readlane_b32 s9, v251, 58
	s_add_u32 s14, s8, 0x5b00000
	s_addc_u32 s15, s9, 0
	s_mulk_i32 s0, 0x1800
	s_add_u32 s0, s14, s0
	s_addc_u32 s1, s15, 0
	s_lshl_b32 s2, s35, 2
	s_and_b32 s2, s2, 0x300
	v_lshlrev_b32_e32 v0, 3, v214
	s_add_u32 s0, s0, s2
	v_and_b32_e32 v0, 0x78, v0
	s_addc_u32 s1, s1, 0
	v_lshlrev_b32_e32 v96, 1, v0
	v_mov_b32_e32 v97, v209
	v_lshl_add_u64 v[2:3], s[0:1], 0, v[96:97]
	v_ashrrev_i32_e32 v0, 4, v214
	v_add_u32_e32 v1, 0x200, v214
	v_mad_i64_i32 v[4:5], s[0:1], v0, s89, v[2:3]
	v_ashrrev_i32_e32 v1, 4, v1
	v_mad_i64_i32 v[2:3], s[0:1], v1, s89, v[2:3]
	s_cmpk_gt_i32 s35, 0x3ff
	s_cbranch_scc1 .LBB0_397
	v_mad_i64_i32 v[98:99], s[0:1], v0, s89, 0
	v_mad_i64_i32 v[100:101], s[0:1], v1, s89, 0
	v_readlane_b32 s0, v252, 0
	v_readlane_b32 s1, v252, 1
	s_lshl_b64 s[0:1], s[0:1], 3
	s_add_u32 s0, s94, s0
	s_addc_u32 s1, s95, s1
	s_load_dwordx2 s[0:1], s[0:1], 0x90
	v_readlane_b32 s2, v252, 5
	v_readlane_b32 s3, v252, 6
	s_lshl_b64 s[2:3], s[2:3], 2
	v_lshlrev_b32_e32 v4, 4, v214
	s_waitcnt lgkmcnt(0)
	s_add_u32 s0, s0, s2
	v_and_b32_e32 v2, 0x70, v4
	s_addc_u32 s1, s1, s3
	v_lshlrev_b32_e32 v208, 2, v2
	v_readlane_b32 s4, v251, 59
	v_lshl_add_u64 v[102:103], s[0:1], 0, v[208:209]
	s_lshl_b32 s0, s4, 5
	v_and_b32_e32 v3, 31, v214
	s_movk_i32 s5, 0x110
	s_and_b32 s0, s0, 0x60
	s_waitcnt vmcnt(0)
	v_mul_lo_u32 v8, v0, s5
	v_or_b32_e32 v0, s0, v3
	v_lshrrev_b32_e32 v6, 5, v235
	v_and_b32_e32 v4, 0xf0, v4
	v_lshlrev_b32_e32 v208, 8, v0
	v_add_u32_e32 v7, 0, v4
	v_mul_lo_u32 v9, v1, s5
	v_lshl_add_u64 v[0:1], s[8:9], 0, v[208:209]
	v_lshlrev_b32_e32 v4, 4, v6
	v_mov_b32_e32 v5, v209
	v_lshl_add_u64 v[0:1], v[0:1], 0, v[4:5]
	s_mov_b64 s[0:1], 0x3a00000
	v_lshl_add_u64 v[104:105], v[0:1], 0, s[0:1]
	s_movk_i32 s0, 0x900
	v_ashrrev_i32_e32 v111, 7, v214
	v_cmp_gt_i32_e64 s[36:37], s0, v214
	s_movk_i32 s0, 0x1100
	v_and_b32_e32 v110, 0x7f, v214
	v_mul_lo_u32 v0, v111, s0
	v_lshlrev_b32_e32 v1, 2, v214
	v_readlane_b32 s0, v251, 1
	v_lshl_add_u32 v113, v110, 1, 0
	v_add_u32_e32 v114, v113, v0
	v_add_u32_e32 v115, s0, v1
	v_lshl_add_u32 v117, v110, 2, s0
	s_movk_i32 s0, 0x7f
	v_lshl_or_b32 v0, v111, 4, 1
	v_mul_u32_u24_e32 v5, 0x90, v110
	v_lshlrev_b32_e32 v10, 5, v111
	v_readlane_b32 s8, v251, 2
	v_cmp_lt_u32_e64 s[38:39], s0, v214
	s_movk_i32 s0, 0x880
	v_lshrrev_b32_e32 v11, 2, v235
	v_mul_lo_u32 v0, v0, s5
	v_add3_u32 v116, s8, v5, v10
	v_mul_lo_u32 v5, v111, s0
	s_cmp_lt_i32 s4, 10
	v_and_b32_e32 v135, 12, v11
	v_or_b32_e32 v5, v5, v110
	v_add_u32_e32 v119, v113, v0
	v_and_b32_e32 v0, 15, v214
	v_readlane_b32 s9, v251, 3
	s_cselect_b64 s[2:3], -1, 0
	v_or_b32_e32 v136, 1, v135
	v_or_b32_e32 v137, 2, v135
	v_or_b32_e32 v138, 3, v11
	s_lshl_b32 s1, s4, 3
	v_lshl_add_u32 v118, v5, 1, 0
	v_lshl_add_u32 v134, v0, 1, s9
	v_mul_u32_u24_e32 v5, 0x110, v0
	v_cmp_gt_u32_e64 s[44:45], v0, v135
	v_cmp_gt_u32_e64 s[46:47], v0, v136
	v_cmp_gt_u32_e64 s[48:49], v0, v137
	v_cmp_gt_u32_e64 s[50:51], v0, v138
	s_bfe_u32 s0, s52, 0x20006
	s_and_b32 s4, s1, 0xffffffe0
	v_mov_b32_e32 v0, s1
	s_movk_i32 s1, 0xffe0
	v_bfi_b32 v0, s1, v0, v214
	s_movk_i32 s1, 0x90
	v_lshl_or_b32 v12, s0, 5, v3
	s_lshl_b32 s0, s0, 7
	v_mul_lo_u32 v11, v0, s1
	v_mov_b32_e32 v13, s8
	v_mul_lo_u32 v0, v0, s5
	s_add_i32 s0, s0, 0
	v_ashrrev_i32_e32 v112, 3, v214
	v_mad_u32_u24 v12, v12, s1, v13
	v_add_u32_e32 v13, 0, v0
	v_lshl_or_b32 v0, v6, 2, s4
	v_lshl_add_u32 v3, v3, 2, s0
	s_movk_i32 s0, 0x210
	v_mul_lo_u32 v6, v0, s0
	v_and_b32_e32 v0, 7, v214
	v_mul_lo_u32 v14, v112, s0
	v_and_b32_e32 v10, 48, v214
	v_add_u32_e32 v11, s9, v11
	v_add_u32_e32 v14, 0, v14
	v_lshlrev_b32_e32 v15, 6, v0
	v_lshlrev_b32_e32 v0, 4, v0
	v_cmp_eq_u32_e64 s[40:41], 2, v111
	v_cmp_eq_u32_e64 s[42:43], 3, v111
	v_add_u32_e32 v120, 0x220, v114
	v_add_u32_e32 v121, 0x330, v114
	v_add_u32_e32 v122, 0x440, v114
	v_add_u32_e32 v123, 0x550, v114
	v_add_u32_e32 v124, 0x660, v114
	v_add_u32_e32 v125, 0x770, v114
	v_add_u32_e32 v126, 0x880, v114
	v_add_u32_e32 v127, 0x990, v114
	v_add_u32_e32 v128, 0xaa0, v114
	v_add_u32_e32 v129, 0xbb0, v114
	v_add_u32_e32 v130, 0xcc0, v114
	v_add_u32_e32 v131, 0xdd0, v114
	v_add_u32_e32 v132, 0xee0, v114
	v_add_u32_e32 v133, 0xff0, v114
	v_add3_u32 v139, 0, v5, v10
	v_add_u32_e32 v140, 0xfffffe00, v214
	v_add_u32_e32 v141, s9, v1
	v_add_u32_e32 v142, v7, v8
	v_add_u32_e32 v143, v7, v9
	v_lshlrev_b32_e32 v208, 1, v2
	v_add_u32_e32 v144, v11, v4
	v_add_u32_e32 v145, v12, v4
	v_add_u32_e32 v146, v13, v4
	v_add_u32_e32 v147, v3, v6
	v_add_u32_e32 v148, v14, v15
	v_lshlrev_b32_e32 v106, 1, v0
	s_mov_b32 s4, s35
	s_branch .LBB0_301

.LBB0_1173:
	s_cmp_eq_u32 s96, 5
	s_cbranch_scc1 .Lh3pf_do
	s_cmp_eq_u32 s96, 14
	s_cbranch_scc0 .Lh3pf_skip
.Lh3pf_do:
	s_mov_b64 s[0:1], exec
	s_mov_b64 exec, -1
	v_readlane_b32 s98, v251, 63
	s_nop 1
	v_mov_b32_e32 v96, s98
	v_readlane_b32 s98, v251, 57
	s_nop 1
	v_mov_b32_e32 v102, s98
	v_readlane_b32 s98, v251, 58
	s_nop 1
	v_mov_b32_e32 v103, s98
	s_mov_b32 s98, 0x5b00000
	s_mov_b32 s99, 0
	v_lshl_add_u64 v[102:103], v[102:103], 0, s[98:99]
	v_lshlrev_b32_e32 v97, 4, v96
	v_and_b32_e32 v97, 0x3000, v97
	v_lshlrev_b32_e32 v98, 6, v96
	v_and_b32_e32 v98, 0xfc0, v98
	v_or_b32_e32 v97, v97, v98
	v_lshlrev_b32_e32 v98, 2, v96
	v_and_b32_e32 v98, 0x300, v98
	v_ashrrev_i32_e32 v99, 4, v122
	v_add_u32_e32 v100, 0x200, v122
	v_ashrrev_i32_e32 v100, 4, v100
	v_add_u32_e32 v99, v97, v99
	v_add_u32_e32 v100, v97, v100
	v_lshlrev_b32_e32 v101, 3, v122
	v_and_b32_e32 v101, 0x78, v101
	v_lshl_add_u32 v96, v101, 1, v98
	v_mov_b32_e32 v97, 0
	v_lshl_add_u64 v[102:103], v[102:103], 0, v[96:97]
	v_mov_b32_e32 v101, 0x1800
	v_mad_u64_u32 v[104:105], s[98:99], v100, v101, v[102:103]
	v_mad_u64_u32 v[102:103], s[98:99], v99, v101, v[102:103]
	global_load_dwordx4 v[72:75], v[102:103], off offset:2048
	global_load_dwordx4 v[76:79], v[104:105], off offset:2048
	global_load_dwordx4 v[80:83], v[102:103], off offset:1024
	global_load_dwordx4 v[84:87], v[104:105], off offset:1024
	global_load_dwordx4 v[88:91], v[102:103], off offset:3072
	global_load_dwordx4 v[92:95], v[104:105], off offset:3072
	s_mov_b64 exec, s[0:1]
